# SCAN: 16 chunk loads in flight per lane instead of 32 (probe: 64 and 8 are worse, 16 slightly better than 32)
# baseline (speedup 1.0000x reference)
.LBB0_521:
.LBB0_522:
	v_lshrrev_b32_e32 v0, 11, v6
	v_and_b32_e32 v0, 12, v0
	s_getpc_b64 s[14:15]
	s_add_u32 s14, s14, _ZN2mk5DEC64E@rel32@lo+4
	s_addc_u32 s15, s15, _ZN2mk5DEC64E@rel32@hi+12
	global_load_dword v0, v0, s[14:15]
	v_lshlrev_b32_e32 v2, 1, v6
	v_bfe_u32 v1, v6, 13, 2
	v_ashrrev_i32_e32 v3, 15, v6
	v_and_b32_e32 v2, 0x3ffe, v2
	v_lshl_or_b32 v7, v3, 8, v1
	v_lshlrev_b32_e32 v8, 1, v2
	v_lshl_or_b32 v12, v7, 15, v8
	v_mov_b32_e32 v4, 0
	v_mov_b32_e32 v5, 0
	global_load_dword v20, v12, s[6:7]
	s_add_u32 s6, s6, 0x20000
	s_addc_u32 s7, s7, 0
	global_load_dword v21, v12, s[6:7]
	s_add_u32 s6, s6, 0x20000
	s_addc_u32 s7, s7, 0
	global_load_dword v22, v12, s[6:7]
	s_add_u32 s6, s6, 0x20000
	s_addc_u32 s7, s7, 0
	global_load_dword v23, v12, s[6:7]
	s_add_u32 s6, s6, 0x20000
	s_addc_u32 s7, s7, 0
	global_load_dword v24, v12, s[6:7]
	s_add_u32 s6, s6, 0x20000
	s_addc_u32 s7, s7, 0
	global_load_dword v25, v12, s[6:7]
	s_add_u32 s6, s6, 0x20000
	s_addc_u32 s7, s7, 0
	global_load_dword v26, v12, s[6:7]
	s_add_u32 s6, s6, 0x20000
	s_addc_u32 s7, s7, 0
	global_load_dword v27, v12, s[6:7]
	s_add_u32 s6, s6, 0x20000
	s_addc_u32 s7, s7, 0
	global_load_dword v28, v12, s[6:7]
	s_add_u32 s6, s6, 0x20000
	s_addc_u32 s7, s7, 0
	global_load_dword v29, v12, s[6:7]
	s_add_u32 s6, s6, 0x20000
	s_addc_u32 s7, s7, 0
	global_load_dword v30, v12, s[6:7]
	s_add_u32 s6, s6, 0x20000
	s_addc_u32 s7, s7, 0
	global_load_dword v31, v12, s[6:7]
	s_add_u32 s6, s6, 0x20000
	s_addc_u32 s7, s7, 0
	global_load_dword v32, v12, s[6:7]
	s_add_u32 s6, s6, 0x20000
	s_addc_u32 s7, s7, 0
	global_load_dword v33, v12, s[6:7]
	s_add_u32 s6, s6, 0x20000
	s_addc_u32 s7, s7, 0
	global_load_dword v34, v12, s[6:7]
	s_add_u32 s6, s6, 0x20000
	s_addc_u32 s7, s7, 0
	global_load_dword v35, v12, s[6:7]
	s_add_u32 s6, s6, 0x20000
	s_addc_u32 s7, s7, 0
	s_waitcnt vmcnt(16)
	v_mov_b32_e32 v1, v0
	s_waitcnt vmcnt(15)
	v_cvt_pk_bf16_f32 v84, v4, v5
	v_lshlrev_b32_e32 v16, 16, v20
	v_and_b32_e32 v17, 0xffff0000, v20
	global_store_dword v12, v84, s[10:11]
	s_add_u32 s10, s10, 0x20000
	s_addc_u32 s11, s11, 0
	v_pk_fma_f32 v[4:5], v[0:1], v[4:5], v[16:17]
	global_load_dword v20, v12, s[6:7]
	s_add_u32 s6, s6, 0x20000
	s_addc_u32 s7, s7, 0
	s_waitcnt vmcnt(16)
	v_cvt_pk_bf16_f32 v85, v4, v5
	v_lshlrev_b32_e32 v16, 16, v21
	v_and_b32_e32 v17, 0xffff0000, v21
	global_store_dword v12, v85, s[10:11]
	s_add_u32 s10, s10, 0x20000
	s_addc_u32 s11, s11, 0
	v_pk_fma_f32 v[4:5], v[0:1], v[4:5], v[16:17]
	global_load_dword v21, v12, s[6:7]
	s_add_u32 s6, s6, 0x20000
	s_addc_u32 s7, s7, 0
	s_waitcnt vmcnt(17)
	v_cvt_pk_bf16_f32 v86, v4, v5
	v_lshlrev_b32_e32 v16, 16, v22
	v_and_b32_e32 v17, 0xffff0000, v22
	global_store_dword v12, v86, s[10:11]
	s_add_u32 s10, s10, 0x20000
	s_addc_u32 s11, s11, 0
	v_pk_fma_f32 v[4:5], v[0:1], v[4:5], v[16:17]
	global_load_dword v22, v12, s[6:7]
	s_add_u32 s6, s6, 0x20000
	s_addc_u32 s7, s7, 0
	s_waitcnt vmcnt(18)
	v_cvt_pk_bf16_f32 v87, v4, v5
	v_lshlrev_b32_e32 v16, 16, v23
	v_and_b32_e32 v17, 0xffff0000, v23
	global_store_dword v12, v87, s[10:11]
	s_add_u32 s10, s10, 0x20000
	s_addc_u32 s11, s11, 0
	v_pk_fma_f32 v[4:5], v[0:1], v[4:5], v[16:17]
	global_load_dword v23, v12, s[6:7]
	s_add_u32 s6, s6, 0x20000
	s_addc_u32 s7, s7, 0
	s_waitcnt vmcnt(19)
	v_cvt_pk_bf16_f32 v88, v4, v5
	v_lshlrev_b32_e32 v16, 16, v24
	v_and_b32_e32 v17, 0xffff0000, v24
	global_store_dword v12, v88, s[10:11]
	s_add_u32 s10, s10, 0x20000
	s_addc_u32 s11, s11, 0
	v_pk_fma_f32 v[4:5], v[0:1], v[4:5], v[16:17]
	global_load_dword v24, v12, s[6:7]
	s_add_u32 s6, s6, 0x20000
	s_addc_u32 s7, s7, 0
	s_waitcnt vmcnt(20)
	v_cvt_pk_bf16_f32 v89, v4, v5
	v_lshlrev_b32_e32 v16, 16, v25
	v_and_b32_e32 v17, 0xffff0000, v25
	global_store_dword v12, v89, s[10:11]
	s_add_u32 s10, s10, 0x20000
	s_addc_u32 s11, s11, 0
	v_pk_fma_f32 v[4:5], v[0:1], v[4:5], v[16:17]
	global_load_dword v25, v12, s[6:7]
	s_add_u32 s6, s6, 0x20000
	s_addc_u32 s7, s7, 0
	s_waitcnt vmcnt(21)
	v_cvt_pk_bf16_f32 v90, v4, v5
	v_lshlrev_b32_e32 v16, 16, v26
	v_and_b32_e32 v17, 0xffff0000, v26
	global_store_dword v12, v90, s[10:11]
	s_add_u32 s10, s10, 0x20000
	s_addc_u32 s11, s11, 0
	v_pk_fma_f32 v[4:5], v[0:1], v[4:5], v[16:17]
	global_load_dword v26, v12, s[6:7]
	s_add_u32 s6, s6, 0x20000
	s_addc_u32 s7, s7, 0
	s_waitcnt vmcnt(22)
	v_cvt_pk_bf16_f32 v91, v4, v5
	v_lshlrev_b32_e32 v16, 16, v27
	v_and_b32_e32 v17, 0xffff0000, v27
	global_store_dword v12, v91, s[10:11]
	s_add_u32 s10, s10, 0x20000
	s_addc_u32 s11, s11, 0
	v_pk_fma_f32 v[4:5], v[0:1], v[4:5], v[16:17]
	global_load_dword v27, v12, s[6:7]
	s_add_u32 s6, s6, 0x20000
	s_addc_u32 s7, s7, 0
	s_waitcnt vmcnt(23)
	v_cvt_pk_bf16_f32 v92, v4, v5
	v_lshlrev_b32_e32 v16, 16, v28
	v_and_b32_e32 v17, 0xffff0000, v28
	global_store_dword v12, v92, s[10:11]
	s_add_u32 s10, s10, 0x20000
	s_addc_u32 s11, s11, 0
	v_pk_fma_f32 v[4:5], v[0:1], v[4:5], v[16:17]
	global_load_dword v28, v12, s[6:7]
	s_add_u32 s6, s6, 0x20000
	s_addc_u32 s7, s7, 0
	s_waitcnt vmcnt(24)
	v_cvt_pk_bf16_f32 v93, v4, v5
	v_lshlrev_b32_e32 v16, 16, v29
	v_and_b32_e32 v17, 0xffff0000, v29
	global_store_dword v12, v93, s[10:11]
	s_add_u32 s10, s10, 0x20000
	s_addc_u32 s11, s11, 0
	v_pk_fma_f32 v[4:5], v[0:1], v[4:5], v[16:17]
	global_load_dword v29, v12, s[6:7]
	s_add_u32 s6, s6, 0x20000
	s_addc_u32 s7, s7, 0
	s_waitcnt vmcnt(25)
	v_cvt_pk_bf16_f32 v94, v4, v5
	v_lshlrev_b32_e32 v16, 16, v30
	v_and_b32_e32 v17, 0xffff0000, v30
	global_store_dword v12, v94, s[10:11]
	s_add_u32 s10, s10, 0x20000
	s_addc_u32 s11, s11, 0
	v_pk_fma_f32 v[4:5], v[0:1], v[4:5], v[16:17]
	global_load_dword v30, v12, s[6:7]
	s_add_u32 s6, s6, 0x20000
	s_addc_u32 s7, s7, 0
	s_waitcnt vmcnt(26)
	v_cvt_pk_bf16_f32 v95, v4, v5
	v_lshlrev_b32_e32 v16, 16, v31
	v_and_b32_e32 v17, 0xffff0000, v31
	global_store_dword v12, v95, s[10:11]
	s_add_u32 s10, s10, 0x20000
	s_addc_u32 s11, s11, 0
	v_pk_fma_f32 v[4:5], v[0:1], v[4:5], v[16:17]
	global_load_dword v31, v12, s[6:7]
	s_add_u32 s6, s6, 0x20000
	s_addc_u32 s7, s7, 0
	s_waitcnt vmcnt(27)
	v_cvt_pk_bf16_f32 v96, v4, v5
	v_lshlrev_b32_e32 v16, 16, v32
	v_and_b32_e32 v17, 0xffff0000, v32
	global_store_dword v12, v96, s[10:11]
	s_add_u32 s10, s10, 0x20000
	s_addc_u32 s11, s11, 0
	v_pk_fma_f32 v[4:5], v[0:1], v[4:5], v[16:17]
	global_load_dword v32, v12, s[6:7]
	s_add_u32 s6, s6, 0x20000
	s_addc_u32 s7, s7, 0
	s_waitcnt vmcnt(28)
	v_cvt_pk_bf16_f32 v97, v4, v5
	v_lshlrev_b32_e32 v16, 16, v33
	v_and_b32_e32 v17, 0xffff0000, v33
	global_store_dword v12, v97, s[10:11]
	s_add_u32 s10, s10, 0x20000
	s_addc_u32 s11, s11, 0
	v_pk_fma_f32 v[4:5], v[0:1], v[4:5], v[16:17]
	global_load_dword v33, v12, s[6:7]
	s_add_u32 s6, s6, 0x20000
	s_addc_u32 s7, s7, 0
	s_waitcnt vmcnt(29)
	v_cvt_pk_bf16_f32 v98, v4, v5
	v_lshlrev_b32_e32 v16, 16, v34
	v_and_b32_e32 v17, 0xffff0000, v34
	global_store_dword v12, v98, s[10:11]
	s_add_u32 s10, s10, 0x20000
	s_addc_u32 s11, s11, 0
	v_pk_fma_f32 v[4:5], v[0:1], v[4:5], v[16:17]
	global_load_dword v34, v12, s[6:7]
	s_add_u32 s6, s6, 0x20000
	s_addc_u32 s7, s7, 0
	s_waitcnt vmcnt(30)
	v_cvt_pk_bf16_f32 v99, v4, v5
	v_lshlrev_b32_e32 v16, 16, v35
	v_and_b32_e32 v17, 0xffff0000, v35
	global_store_dword v12, v99, s[10:11]
	s_add_u32 s10, s10, 0x20000
	s_addc_u32 s11, s11, 0
	v_pk_fma_f32 v[4:5], v[0:1], v[4:5], v[16:17]
	global_load_dword v35, v12, s[6:7]
	s_add_u32 s6, s6, 0x20000
	s_addc_u32 s7, s7, 0
	s_waitcnt vmcnt(30)
	v_cvt_pk_bf16_f32 v100, v4, v5
	v_lshlrev_b32_e32 v16, 16, v20
	v_and_b32_e32 v17, 0xffff0000, v20
	global_store_dword v12, v100, s[10:11]
	s_add_u32 s10, s10, 0x20000
	s_addc_u32 s11, s11, 0
	v_pk_fma_f32 v[4:5], v[0:1], v[4:5], v[16:17]
	global_load_dword v20, v12, s[6:7]
	s_add_u32 s6, s6, 0x20000
	s_addc_u32 s7, s7, 0
	s_waitcnt vmcnt(30)
	v_cvt_pk_bf16_f32 v101, v4, v5
	v_lshlrev_b32_e32 v16, 16, v21
	v_and_b32_e32 v17, 0xffff0000, v21
	global_store_dword v12, v101, s[10:11]
	s_add_u32 s10, s10, 0x20000
	s_addc_u32 s11, s11, 0
	v_pk_fma_f32 v[4:5], v[0:1], v[4:5], v[16:17]
	global_load_dword v21, v12, s[6:7]
	s_add_u32 s6, s6, 0x20000
	s_addc_u32 s7, s7, 0
	s_waitcnt vmcnt(30)
	v_cvt_pk_bf16_f32 v102, v4, v5
	v_lshlrev_b32_e32 v16, 16, v22
	v_and_b32_e32 v17, 0xffff0000, v22
	global_store_dword v12, v102, s[10:11]
	s_add_u32 s10, s10, 0x20000
	s_addc_u32 s11, s11, 0
	v_pk_fma_f32 v[4:5], v[0:1], v[4:5], v[16:17]
	global_load_dword v22, v12, s[6:7]
	s_add_u32 s6, s6, 0x20000
	s_addc_u32 s7, s7, 0
	s_waitcnt vmcnt(30)
	v_cvt_pk_bf16_f32 v103, v4, v5
	v_lshlrev_b32_e32 v16, 16, v23
	v_and_b32_e32 v17, 0xffff0000, v23
	global_store_dword v12, v103, s[10:11]
	s_add_u32 s10, s10, 0x20000
	s_addc_u32 s11, s11, 0
	v_pk_fma_f32 v[4:5], v[0:1], v[4:5], v[16:17]
	global_load_dword v23, v12, s[6:7]
	s_add_u32 s6, s6, 0x20000
	s_addc_u32 s7, s7, 0
	s_waitcnt vmcnt(30)
	v_cvt_pk_bf16_f32 v104, v4, v5
	v_lshlrev_b32_e32 v16, 16, v24
	v_and_b32_e32 v17, 0xffff0000, v24
	global_store_dword v12, v104, s[10:11]
	s_add_u32 s10, s10, 0x20000
	s_addc_u32 s11, s11, 0
	v_pk_fma_f32 v[4:5], v[0:1], v[4:5], v[16:17]
	global_load_dword v24, v12, s[6:7]
	s_add_u32 s6, s6, 0x20000
	s_addc_u32 s7, s7, 0
	s_waitcnt vmcnt(30)
	v_cvt_pk_bf16_f32 v105, v4, v5
	v_lshlrev_b32_e32 v16, 16, v25
	v_and_b32_e32 v17, 0xffff0000, v25
	global_store_dword v12, v105, s[10:11]
	s_add_u32 s10, s10, 0x20000
	s_addc_u32 s11, s11, 0
	v_pk_fma_f32 v[4:5], v[0:1], v[4:5], v[16:17]
	global_load_dword v25, v12, s[6:7]
	s_add_u32 s6, s6, 0x20000
	s_addc_u32 s7, s7, 0
	s_waitcnt vmcnt(30)
	v_cvt_pk_bf16_f32 v106, v4, v5
	v_lshlrev_b32_e32 v16, 16, v26
	v_and_b32_e32 v17, 0xffff0000, v26
	global_store_dword v12, v106, s[10:11]
	s_add_u32 s10, s10, 0x20000
	s_addc_u32 s11, s11, 0
	v_pk_fma_f32 v[4:5], v[0:1], v[4:5], v[16:17]
	global_load_dword v26, v12, s[6:7]
	s_add_u32 s6, s6, 0x20000
	s_addc_u32 s7, s7, 0
	s_waitcnt vmcnt(30)
	v_cvt_pk_bf16_f32 v107, v4, v5
	v_lshlrev_b32_e32 v16, 16, v27
	v_and_b32_e32 v17, 0xffff0000, v27
	global_store_dword v12, v107, s[10:11]
	s_add_u32 s10, s10, 0x20000
	s_addc_u32 s11, s11, 0
	v_pk_fma_f32 v[4:5], v[0:1], v[4:5], v[16:17]
	global_load_dword v27, v12, s[6:7]
	s_add_u32 s6, s6, 0x20000
	s_addc_u32 s7, s7, 0
	s_waitcnt vmcnt(30)
	v_cvt_pk_bf16_f32 v108, v4, v5
	v_lshlrev_b32_e32 v16, 16, v28
	v_and_b32_e32 v17, 0xffff0000, v28
	global_store_dword v12, v108, s[10:11]
	s_add_u32 s10, s10, 0x20000
	s_addc_u32 s11, s11, 0
	v_pk_fma_f32 v[4:5], v[0:1], v[4:5], v[16:17]
	global_load_dword v28, v12, s[6:7]
	s_add_u32 s6, s6, 0x20000
	s_addc_u32 s7, s7, 0
	s_waitcnt vmcnt(30)
	v_cvt_pk_bf16_f32 v109, v4, v5
	v_lshlrev_b32_e32 v16, 16, v29
	v_and_b32_e32 v17, 0xffff0000, v29
	global_store_dword v12, v109, s[10:11]
	s_add_u32 s10, s10, 0x20000
	s_addc_u32 s11, s11, 0
	v_pk_fma_f32 v[4:5], v[0:1], v[4:5], v[16:17]
	global_load_dword v29, v12, s[6:7]
	s_add_u32 s6, s6, 0x20000
	s_addc_u32 s7, s7, 0
	s_waitcnt vmcnt(30)
	v_cvt_pk_bf16_f32 v110, v4, v5
	v_lshlrev_b32_e32 v16, 16, v30
	v_and_b32_e32 v17, 0xffff0000, v30
	global_store_dword v12, v110, s[10:11]
	s_add_u32 s10, s10, 0x20000
	s_addc_u32 s11, s11, 0
	v_pk_fma_f32 v[4:5], v[0:1], v[4:5], v[16:17]
	global_load_dword v30, v12, s[6:7]
	s_add_u32 s6, s6, 0x20000
	s_addc_u32 s7, s7, 0
	s_waitcnt vmcnt(30)
	v_cvt_pk_bf16_f32 v111, v4, v5
	v_lshlrev_b32_e32 v16, 16, v31
	v_and_b32_e32 v17, 0xffff0000, v31
	global_store_dword v12, v111, s[10:11]
	s_add_u32 s10, s10, 0x20000
	s_addc_u32 s11, s11, 0
	v_pk_fma_f32 v[4:5], v[0:1], v[4:5], v[16:17]
	global_load_dword v31, v12, s[6:7]
	s_add_u32 s6, s6, 0x20000
	s_addc_u32 s7, s7, 0
	s_waitcnt vmcnt(30)
	v_cvt_pk_bf16_f32 v112, v4, v5
	v_lshlrev_b32_e32 v16, 16, v32
	v_and_b32_e32 v17, 0xffff0000, v32
	global_store_dword v12, v112, s[10:11]
	s_add_u32 s10, s10, 0x20000
	s_addc_u32 s11, s11, 0
	v_pk_fma_f32 v[4:5], v[0:1], v[4:5], v[16:17]
	global_load_dword v32, v12, s[6:7]
	s_add_u32 s6, s6, 0x20000
	s_addc_u32 s7, s7, 0
	s_waitcnt vmcnt(30)
	v_cvt_pk_bf16_f32 v113, v4, v5
	v_lshlrev_b32_e32 v16, 16, v33
	v_and_b32_e32 v17, 0xffff0000, v33
	global_store_dword v12, v113, s[10:11]
	s_add_u32 s10, s10, 0x20000
	s_addc_u32 s11, s11, 0
	v_pk_fma_f32 v[4:5], v[0:1], v[4:5], v[16:17]
	global_load_dword v33, v12, s[6:7]
	s_add_u32 s6, s6, 0x20000
	s_addc_u32 s7, s7, 0
	s_waitcnt vmcnt(30)
	v_cvt_pk_bf16_f32 v114, v4, v5
	v_lshlrev_b32_e32 v16, 16, v34
	v_and_b32_e32 v17, 0xffff0000, v34
	global_store_dword v12, v114, s[10:11]
	s_add_u32 s10, s10, 0x20000
	s_addc_u32 s11, s11, 0
	v_pk_fma_f32 v[4:5], v[0:1], v[4:5], v[16:17]
	global_load_dword v34, v12, s[6:7]
	s_add_u32 s6, s6, 0x20000
	s_addc_u32 s7, s7, 0
	s_waitcnt vmcnt(30)
	v_cvt_pk_bf16_f32 v115, v4, v5
	v_lshlrev_b32_e32 v16, 16, v35
	v_and_b32_e32 v17, 0xffff0000, v35
	global_store_dword v12, v115, s[10:11]
	s_add_u32 s10, s10, 0x20000
	s_addc_u32 s11, s11, 0
	v_pk_fma_f32 v[4:5], v[0:1], v[4:5], v[16:17]
	global_load_dword v35, v12, s[6:7]
	s_add_u32 s6, s6, 0x20000
	s_addc_u32 s7, s7, 0
	s_waitcnt vmcnt(30)
	v_cvt_pk_bf16_f32 v116, v4, v5
	v_lshlrev_b32_e32 v16, 16, v20
	v_and_b32_e32 v17, 0xffff0000, v20
	global_store_dword v12, v116, s[10:11]
	s_add_u32 s10, s10, 0x20000
	s_addc_u32 s11, s11, 0
	v_pk_fma_f32 v[4:5], v[0:1], v[4:5], v[16:17]
	global_load_dword v20, v12, s[6:7]
	s_add_u32 s6, s6, 0x20000
	s_addc_u32 s7, s7, 0
	s_waitcnt vmcnt(30)
	v_cvt_pk_bf16_f32 v117, v4, v5
	v_lshlrev_b32_e32 v16, 16, v21
	v_and_b32_e32 v17, 0xffff0000, v21
	global_store_dword v12, v117, s[10:11]
	s_add_u32 s10, s10, 0x20000
	s_addc_u32 s11, s11, 0
	v_pk_fma_f32 v[4:5], v[0:1], v[4:5], v[16:17]
	global_load_dword v21, v12, s[6:7]
	s_add_u32 s6, s6, 0x20000
	s_addc_u32 s7, s7, 0
	s_waitcnt vmcnt(30)
	v_cvt_pk_bf16_f32 v118, v4, v5
	v_lshlrev_b32_e32 v16, 16, v22
	v_and_b32_e32 v17, 0xffff0000, v22
	global_store_dword v12, v118, s[10:11]
	s_add_u32 s10, s10, 0x20000
	s_addc_u32 s11, s11, 0
	v_pk_fma_f32 v[4:5], v[0:1], v[4:5], v[16:17]
	global_load_dword v22, v12, s[6:7]
	s_add_u32 s6, s6, 0x20000
	s_addc_u32 s7, s7, 0
	s_waitcnt vmcnt(30)
	v_cvt_pk_bf16_f32 v119, v4, v5
	v_lshlrev_b32_e32 v16, 16, v23
	v_and_b32_e32 v17, 0xffff0000, v23
	global_store_dword v12, v119, s[10:11]
	s_add_u32 s10, s10, 0x20000
	s_addc_u32 s11, s11, 0
	v_pk_fma_f32 v[4:5], v[0:1], v[4:5], v[16:17]
	global_load_dword v23, v12, s[6:7]
	s_add_u32 s6, s6, 0x20000
	s_addc_u32 s7, s7, 0
	s_waitcnt vmcnt(30)
	v_cvt_pk_bf16_f32 v120, v4, v5
	v_lshlrev_b32_e32 v16, 16, v24
	v_and_b32_e32 v17, 0xffff0000, v24
	global_store_dword v12, v120, s[10:11]
	s_add_u32 s10, s10, 0x20000
	s_addc_u32 s11, s11, 0
	v_pk_fma_f32 v[4:5], v[0:1], v[4:5], v[16:17]
	global_load_dword v24, v12, s[6:7]
	s_add_u32 s6, s6, 0x20000
	s_addc_u32 s7, s7, 0
	s_waitcnt vmcnt(30)
	v_cvt_pk_bf16_f32 v121, v4, v5
	v_lshlrev_b32_e32 v16, 16, v25
	v_and_b32_e32 v17, 0xffff0000, v25
	global_store_dword v12, v121, s[10:11]
	s_add_u32 s10, s10, 0x20000
	s_addc_u32 s11, s11, 0
	v_pk_fma_f32 v[4:5], v[0:1], v[4:5], v[16:17]
	global_load_dword v25, v12, s[6:7]
	s_add_u32 s6, s6, 0x20000
	s_addc_u32 s7, s7, 0
	s_waitcnt vmcnt(30)
	v_cvt_pk_bf16_f32 v122, v4, v5
	v_lshlrev_b32_e32 v16, 16, v26
	v_and_b32_e32 v17, 0xffff0000, v26
	global_store_dword v12, v122, s[10:11]
	s_add_u32 s10, s10, 0x20000
	s_addc_u32 s11, s11, 0
	v_pk_fma_f32 v[4:5], v[0:1], v[4:5], v[16:17]
	global_load_dword v26, v12, s[6:7]
	s_add_u32 s6, s6, 0x20000
	s_addc_u32 s7, s7, 0
	s_waitcnt vmcnt(30)
	v_cvt_pk_bf16_f32 v123, v4, v5
	v_lshlrev_b32_e32 v16, 16, v27
	v_and_b32_e32 v17, 0xffff0000, v27
	global_store_dword v12, v123, s[10:11]
	s_add_u32 s10, s10, 0x20000
	s_addc_u32 s11, s11, 0
	v_pk_fma_f32 v[4:5], v[0:1], v[4:5], v[16:17]
	global_load_dword v27, v12, s[6:7]
	s_add_u32 s6, s6, 0x20000
	s_addc_u32 s7, s7, 0
	s_waitcnt vmcnt(30)
	v_cvt_pk_bf16_f32 v124, v4, v5
	v_lshlrev_b32_e32 v16, 16, v28
	v_and_b32_e32 v17, 0xffff0000, v28
	global_store_dword v12, v124, s[10:11]
	s_add_u32 s10, s10, 0x20000
	s_addc_u32 s11, s11, 0
	v_pk_fma_f32 v[4:5], v[0:1], v[4:5], v[16:17]
	global_load_dword v28, v12, s[6:7]
	s_add_u32 s6, s6, 0x20000
	s_addc_u32 s7, s7, 0
	s_waitcnt vmcnt(30)
	v_cvt_pk_bf16_f32 v125, v4, v5
	v_lshlrev_b32_e32 v16, 16, v29
	v_and_b32_e32 v17, 0xffff0000, v29
	global_store_dword v12, v125, s[10:11]
	s_add_u32 s10, s10, 0x20000
	s_addc_u32 s11, s11, 0
	v_pk_fma_f32 v[4:5], v[0:1], v[4:5], v[16:17]
	global_load_dword v29, v12, s[6:7]
	s_add_u32 s6, s6, 0x20000
	s_addc_u32 s7, s7, 0
	s_waitcnt vmcnt(30)
	v_cvt_pk_bf16_f32 v126, v4, v5
	v_lshlrev_b32_e32 v16, 16, v30
	v_and_b32_e32 v17, 0xffff0000, v30
	global_store_dword v12, v126, s[10:11]
	s_add_u32 s10, s10, 0x20000
	s_addc_u32 s11, s11, 0
	v_pk_fma_f32 v[4:5], v[0:1], v[4:5], v[16:17]
	global_load_dword v30, v12, s[6:7]
	s_add_u32 s6, s6, 0x20000
	s_addc_u32 s7, s7, 0
	s_waitcnt vmcnt(30)
	v_cvt_pk_bf16_f32 v127, v4, v5
	v_lshlrev_b32_e32 v16, 16, v31
	v_and_b32_e32 v17, 0xffff0000, v31
	global_store_dword v12, v127, s[10:11]
	s_add_u32 s10, s10, 0x20000
	s_addc_u32 s11, s11, 0
	v_pk_fma_f32 v[4:5], v[0:1], v[4:5], v[16:17]
	global_load_dword v31, v12, s[6:7]
	s_add_u32 s6, s6, 0x20000
	s_addc_u32 s7, s7, 0
	s_waitcnt vmcnt(30)
	v_cvt_pk_bf16_f32 v128, v4, v5
	v_lshlrev_b32_e32 v16, 16, v32
	v_and_b32_e32 v17, 0xffff0000, v32
	global_store_dword v12, v128, s[10:11]
	s_add_u32 s10, s10, 0x20000
	s_addc_u32 s11, s11, 0
	v_pk_fma_f32 v[4:5], v[0:1], v[4:5], v[16:17]
	global_load_dword v32, v12, s[6:7]
	s_add_u32 s6, s6, 0x20000
	s_addc_u32 s7, s7, 0
	s_waitcnt vmcnt(30)
	v_cvt_pk_bf16_f32 v129, v4, v5
	v_lshlrev_b32_e32 v16, 16, v33
	v_and_b32_e32 v17, 0xffff0000, v33
	global_store_dword v12, v129, s[10:11]
	s_add_u32 s10, s10, 0x20000
	s_addc_u32 s11, s11, 0
	v_pk_fma_f32 v[4:5], v[0:1], v[4:5], v[16:17]
	global_load_dword v33, v12, s[6:7]
	s_add_u32 s6, s6, 0x20000
	s_addc_u32 s7, s7, 0
	s_waitcnt vmcnt(30)
	v_cvt_pk_bf16_f32 v130, v4, v5
	v_lshlrev_b32_e32 v16, 16, v34
	v_and_b32_e32 v17, 0xffff0000, v34
	global_store_dword v12, v130, s[10:11]
	s_add_u32 s10, s10, 0x20000
	s_addc_u32 s11, s11, 0
	v_pk_fma_f32 v[4:5], v[0:1], v[4:5], v[16:17]
	global_load_dword v34, v12, s[6:7]
	s_add_u32 s6, s6, 0x20000
	s_addc_u32 s7, s7, 0
	s_waitcnt vmcnt(30)
	v_cvt_pk_bf16_f32 v131, v4, v5
	v_lshlrev_b32_e32 v16, 16, v35
	v_and_b32_e32 v17, 0xffff0000, v35
	global_store_dword v12, v131, s[10:11]
	s_add_u32 s10, s10, 0x20000
	s_addc_u32 s11, s11, 0
	v_pk_fma_f32 v[4:5], v[0:1], v[4:5], v[16:17]
	global_load_dword v35, v12, s[6:7]
	s_add_u32 s6, s6, 0x20000
	s_addc_u32 s7, s7, 0
	s_waitcnt vmcnt(30)
	v_cvt_pk_bf16_f32 v132, v4, v5
	v_lshlrev_b32_e32 v16, 16, v20
	v_and_b32_e32 v17, 0xffff0000, v20
	global_store_dword v12, v132, s[10:11]
	s_add_u32 s10, s10, 0x20000
	s_addc_u32 s11, s11, 0
	v_pk_fma_f32 v[4:5], v[0:1], v[4:5], v[16:17]
	s_waitcnt vmcnt(29)
	v_cvt_pk_bf16_f32 v133, v4, v5
	v_lshlrev_b32_e32 v16, 16, v21
	v_and_b32_e32 v17, 0xffff0000, v21
	global_store_dword v12, v133, s[10:11]
	s_add_u32 s10, s10, 0x20000
	s_addc_u32 s11, s11, 0
	v_pk_fma_f32 v[4:5], v[0:1], v[4:5], v[16:17]
	s_waitcnt vmcnt(28)
	v_cvt_pk_bf16_f32 v134, v4, v5
	v_lshlrev_b32_e32 v16, 16, v22
	v_and_b32_e32 v17, 0xffff0000, v22
	global_store_dword v12, v134, s[10:11]
	s_add_u32 s10, s10, 0x20000
	s_addc_u32 s11, s11, 0
	v_pk_fma_f32 v[4:5], v[0:1], v[4:5], v[16:17]
	s_waitcnt vmcnt(27)
	v_cvt_pk_bf16_f32 v135, v4, v5
	v_lshlrev_b32_e32 v16, 16, v23
	v_and_b32_e32 v17, 0xffff0000, v23
	global_store_dword v12, v135, s[10:11]
	s_add_u32 s10, s10, 0x20000
	s_addc_u32 s11, s11, 0
	v_pk_fma_f32 v[4:5], v[0:1], v[4:5], v[16:17]
	s_waitcnt vmcnt(26)
	v_cvt_pk_bf16_f32 v136, v4, v5
	v_lshlrev_b32_e32 v16, 16, v24
	v_and_b32_e32 v17, 0xffff0000, v24
	global_store_dword v12, v136, s[10:11]
	s_add_u32 s10, s10, 0x20000
	s_addc_u32 s11, s11, 0
	v_pk_fma_f32 v[4:5], v[0:1], v[4:5], v[16:17]
	s_waitcnt vmcnt(25)
	v_cvt_pk_bf16_f32 v137, v4, v5
	v_lshlrev_b32_e32 v16, 16, v25
	v_and_b32_e32 v17, 0xffff0000, v25
	global_store_dword v12, v137, s[10:11]
	s_add_u32 s10, s10, 0x20000
	s_addc_u32 s11, s11, 0
	v_pk_fma_f32 v[4:5], v[0:1], v[4:5], v[16:17]
	s_waitcnt vmcnt(24)
	v_cvt_pk_bf16_f32 v138, v4, v5
	v_lshlrev_b32_e32 v16, 16, v26
	v_and_b32_e32 v17, 0xffff0000, v26
	global_store_dword v12, v138, s[10:11]
	s_add_u32 s10, s10, 0x20000
	s_addc_u32 s11, s11, 0
	v_pk_fma_f32 v[4:5], v[0:1], v[4:5], v[16:17]
	s_waitcnt vmcnt(23)
	v_cvt_pk_bf16_f32 v139, v4, v5
	v_lshlrev_b32_e32 v16, 16, v27
	v_and_b32_e32 v17, 0xffff0000, v27
	global_store_dword v12, v139, s[10:11]
	s_add_u32 s10, s10, 0x20000
	s_addc_u32 s11, s11, 0
	v_pk_fma_f32 v[4:5], v[0:1], v[4:5], v[16:17]
	s_waitcnt vmcnt(22)
	v_cvt_pk_bf16_f32 v140, v4, v5
	v_lshlrev_b32_e32 v16, 16, v28
	v_and_b32_e32 v17, 0xffff0000, v28
	global_store_dword v12, v140, s[10:11]
	s_add_u32 s10, s10, 0x20000
	s_addc_u32 s11, s11, 0
	v_pk_fma_f32 v[4:5], v[0:1], v[4:5], v[16:17]
	s_waitcnt vmcnt(21)
	v_cvt_pk_bf16_f32 v141, v4, v5
	v_lshlrev_b32_e32 v16, 16, v29
	v_and_b32_e32 v17, 0xffff0000, v29
	global_store_dword v12, v141, s[10:11]
	s_add_u32 s10, s10, 0x20000
	s_addc_u32 s11, s11, 0
	v_pk_fma_f32 v[4:5], v[0:1], v[4:5], v[16:17]
	s_waitcnt vmcnt(20)
	v_cvt_pk_bf16_f32 v142, v4, v5
	v_lshlrev_b32_e32 v16, 16, v30
	v_and_b32_e32 v17, 0xffff0000, v30
	global_store_dword v12, v142, s[10:11]
	s_add_u32 s10, s10, 0x20000
	s_addc_u32 s11, s11, 0
	v_pk_fma_f32 v[4:5], v[0:1], v[4:5], v[16:17]
	s_waitcnt vmcnt(19)
	v_cvt_pk_bf16_f32 v143, v4, v5
	v_lshlrev_b32_e32 v16, 16, v31
	v_and_b32_e32 v17, 0xffff0000, v31
	global_store_dword v12, v143, s[10:11]
	s_add_u32 s10, s10, 0x20000
	s_addc_u32 s11, s11, 0
	v_pk_fma_f32 v[4:5], v[0:1], v[4:5], v[16:17]
	s_waitcnt vmcnt(18)
	v_cvt_pk_bf16_f32 v144, v4, v5
	v_lshlrev_b32_e32 v16, 16, v32
	v_and_b32_e32 v17, 0xffff0000, v32
	global_store_dword v12, v144, s[10:11]
	s_add_u32 s10, s10, 0x20000
	s_addc_u32 s11, s11, 0
	v_pk_fma_f32 v[4:5], v[0:1], v[4:5], v[16:17]
	s_waitcnt vmcnt(17)
	v_cvt_pk_bf16_f32 v145, v4, v5
	v_lshlrev_b32_e32 v16, 16, v33
	v_and_b32_e32 v17, 0xffff0000, v33
	global_store_dword v12, v145, s[10:11]
	s_add_u32 s10, s10, 0x20000
	s_addc_u32 s11, s11, 0
	v_pk_fma_f32 v[4:5], v[0:1], v[4:5], v[16:17]
	s_waitcnt vmcnt(16)
	v_cvt_pk_bf16_f32 v146, v4, v5
	v_lshlrev_b32_e32 v16, 16, v34
	v_and_b32_e32 v17, 0xffff0000, v34
	global_store_dword v12, v146, s[10:11]
	s_add_u32 s10, s10, 0x20000
	s_addc_u32 s11, s11, 0
	v_pk_fma_f32 v[4:5], v[0:1], v[4:5], v[16:17]
	s_waitcnt vmcnt(15)
	v_cvt_pk_bf16_f32 v147, v4, v5
	v_lshlrev_b32_e32 v16, 16, v35
	v_and_b32_e32 v17, 0xffff0000, v35
	global_store_dword v12, v147, s[10:11]
	s_add_u32 s10, s10, 0x20000
	s_addc_u32 s11, s11, 0
	v_pk_fma_f32 v[4:5], v[0:1], v[4:5], v[16:17]
